# v20 + pool unit second half waits only for its 8 weight loads (vmcnt 15..8) instead of draining the first half's 8 output stores
# speedup vs baseline: 1.0082x; 1.0082x over previous
.LBB0_177:
	s_xor_b64 s[0:1], s[0:1], -1
	s_and_b64 vcc, exec, s[0:1]
	s_cbranch_vccnz .Lpool_h1
	s_waitcnt vmcnt(7)
	ds_write_b128 v52, v[2:5]
	s_waitcnt vmcnt(6)
	ds_write_b128 v53, v[6:9]
	s_waitcnt vmcnt(5)
	ds_write_b128 v54, v[10:13]
	s_waitcnt vmcnt(4)
	ds_write_b128 v55, v[14:17]
	s_waitcnt vmcnt(3)
	ds_write_b128 v56, v[18:21]
	s_waitcnt vmcnt(2)
	ds_write_b128 v57, v[22:25]
	s_waitcnt vmcnt(1)
	ds_write_b128 v58, v[26:29]
	s_waitcnt vmcnt(0)
	ds_write_b128 v0, v[30:33]
	global_load_dwordx4 v[2:5], v[36:37], off
	global_load_dwordx4 v[6:9], v[38:39], off
	global_load_dwordx4 v[10:13], v[40:41], off
	global_load_dwordx4 v[14:17], v[42:43], off
	global_load_dwordx4 v[18:21], v[44:45], off
	global_load_dwordx4 v[22:25], v[46:47], off
	global_load_dwordx4 v[26:29], v[48:49], off
	global_load_dwordx4 v[30:33], v[50:51], off
	s_branch .LBB0_176
.Lpool_h1:
	s_waitcnt vmcnt(15)
	ds_write_b128 v52, v[2:5]
	s_waitcnt vmcnt(14)
	ds_write_b128 v53, v[6:9]
	s_waitcnt vmcnt(13)
	ds_write_b128 v54, v[10:13]
	s_waitcnt vmcnt(12)
	ds_write_b128 v55, v[14:17]
	s_waitcnt vmcnt(11)
	ds_write_b128 v56, v[18:21]
	s_waitcnt vmcnt(10)
	ds_write_b128 v57, v[22:25]
	s_waitcnt vmcnt(9)
	ds_write_b128 v58, v[26:29]
	s_waitcnt vmcnt(8)
	ds_write_b128 v0, v[30:33]
	s_branch .LBB0_176
